# out-proj/FF2 K-loop: in the second-to-last iteration touch half of the residual tile (rows 0-127) so the epilogue reads it from L2
# speedup vs baseline: 1.0116x; 1.0028x over previous
.LBB0_228:
	s_and_b32 s48, s48, 7
	s_or_b32 s73, s48, s4
	s_and_b64 s[48:49], s[46:47], exec
	s_cselect_b32 s48, s73, s29
	s_ashr_i32 s49, s48, 31
	s_lshl_b64 s[48:49], s[48:49], 21
	v_readlane_b32 s29, v236, 61
	s_add_u32 s48, s29, s48
	v_readlane_b32 s29, v236, 58
	v_mov_b32_e32 v125, 0
	s_addc_u32 s49, s29, s49
	s_andn2_b64 vcc, exec, s[42:43]
	v_mov_b32_e32 v124, v125
	v_mov_b32_e32 v123, v125
	v_mov_b32_e32 v122, v125
	v_mov_b32_e32 v129, v125
	v_mov_b32_e32 v128, v125
	v_mov_b32_e32 v127, v125
	v_mov_b32_e32 v126, v125
	v_mov_b32_e32 v113, v125
	v_mov_b32_e32 v112, v125
	v_mov_b32_e32 v111, v125
	v_mov_b32_e32 v110, v125
	v_mov_b32_e32 v109, v125
	v_mov_b32_e32 v108, v125
	v_mov_b32_e32 v107, v125
	v_mov_b32_e32 v106, v125
	v_mov_b32_e32 v97, v125
	v_mov_b32_e32 v96, v125
	v_mov_b32_e32 v95, v125
	v_mov_b32_e32 v94, v125
	v_mov_b32_e32 v93, v125
	v_mov_b32_e32 v92, v125
	v_mov_b32_e32 v91, v125
	v_mov_b32_e32 v90, v125
	v_mov_b32_e32 v81, v125
	v_mov_b32_e32 v80, v125
	v_mov_b32_e32 v79, v125
	v_mov_b32_e32 v78, v125
	v_mov_b32_e32 v77, v125
	v_mov_b32_e32 v76, v125
	v_mov_b32_e32 v75, v125
	v_mov_b32_e32 v74, v125
	v_mov_b32_e32 v121, v125
	v_mov_b32_e32 v120, v125
	v_mov_b32_e32 v119, v125
	v_mov_b32_e32 v118, v125
	v_mov_b32_e32 v117, v125
	v_mov_b32_e32 v116, v125
	v_mov_b32_e32 v115, v125
	v_mov_b32_e32 v114, v125
	v_mov_b32_e32 v105, v125
	v_mov_b32_e32 v104, v125
	v_mov_b32_e32 v103, v125
	v_mov_b32_e32 v102, v125
	v_mov_b32_e32 v101, v125
	v_mov_b32_e32 v100, v125
	v_mov_b32_e32 v99, v125
	v_mov_b32_e32 v98, v125
	v_mov_b32_e32 v89, v125
	v_mov_b32_e32 v88, v125
	v_mov_b32_e32 v87, v125
	v_mov_b32_e32 v86, v125
	v_mov_b32_e32 v85, v125
	v_mov_b32_e32 v84, v125
	v_mov_b32_e32 v83, v125
	v_mov_b32_e32 v82, v125
	v_mov_b32_e32 v73, v125
	v_mov_b32_e32 v72, v125
	v_mov_b32_e32 v71, v125
	v_mov_b32_e32 v70, v125
	v_mov_b32_e32 v69, v125
	v_mov_b32_e32 v68, v125
	v_mov_b32_e32 v67, v125
	v_mov_b32_e32 v66, v125
	v_mov_b32_e32 v65, v125
	v_mov_b32_e32 v64, v125
	v_mov_b32_e32 v63, v125
	v_mov_b32_e32 v62, v125
	v_mov_b32_e32 v61, v125
	v_mov_b32_e32 v60, v125
	v_mov_b32_e32 v59, v125
	v_mov_b32_e32 v58, v125
	v_mov_b32_e32 v49, v125
	v_mov_b32_e32 v48, v125
	v_mov_b32_e32 v47, v125
	v_mov_b32_e32 v46, v125
	v_mov_b32_e32 v45, v125
	v_mov_b32_e32 v44, v125
	v_mov_b32_e32 v43, v125
	v_mov_b32_e32 v42, v125
	v_mov_b32_e32 v33, v125
	v_mov_b32_e32 v32, v125
	v_mov_b32_e32 v31, v125
	v_mov_b32_e32 v30, v125
	v_mov_b32_e32 v29, v125
	v_mov_b32_e32 v28, v125
	v_mov_b32_e32 v27, v125
	v_mov_b32_e32 v26, v125
	v_mov_b32_e32 v17, v125
	v_mov_b32_e32 v16, v125
	v_mov_b32_e32 v15, v125
	v_mov_b32_e32 v14, v125
	v_mov_b32_e32 v13, v125
	v_mov_b32_e32 v12, v125
	v_mov_b32_e32 v11, v125
	v_mov_b32_e32 v10, v125
	v_mov_b32_e32 v57, v125
	v_mov_b32_e32 v56, v125
	v_mov_b32_e32 v55, v125
	v_mov_b32_e32 v54, v125
	v_mov_b32_e32 v53, v125
	v_mov_b32_e32 v52, v125
	v_mov_b32_e32 v51, v125
	v_mov_b32_e32 v50, v125
	v_mov_b32_e32 v41, v125
	v_mov_b32_e32 v40, v125
	v_mov_b32_e32 v39, v125
	v_mov_b32_e32 v38, v125
	v_mov_b32_e32 v37, v125
	v_mov_b32_e32 v36, v125
	v_mov_b32_e32 v35, v125
	v_mov_b32_e32 v34, v125
	v_mov_b32_e32 v25, v125
	v_mov_b32_e32 v24, v125
	v_mov_b32_e32 v23, v125
	v_mov_b32_e32 v22, v125
	v_mov_b32_e32 v21, v125
	v_mov_b32_e32 v20, v125
	v_mov_b32_e32 v19, v125
	v_mov_b32_e32 v18, v125
	v_mov_b32_e32 v9, v125
	v_mov_b32_e32 v8, v125
	v_mov_b32_e32 v7, v125
	v_mov_b32_e32 v6, v125
	v_mov_b32_e32 v5, v125
	v_mov_b32_e32 v4, v125
	s_waitcnt lgkmcnt(0)
	v_mov_b32_e32 v3, v125
	v_mov_b32_e32 v2, v125
	s_cbranch_vccnz .LBB0_232
	s_and_b64 s[50:51], s[46:47], exec
	s_cselect_b32 s29, s49, s57
	s_cselect_b32 s50, s48, s56
	s_add_u32 s56, s56, 0x80
	s_addc_u32 s57, s57, 0
	s_add_u32 s51, s58, 0x100
	v_mov_b32_e32 v2, 0
	s_addc_u32 s55, s59, 0
	s_mov_b32 s58, 0
	v_mov_b32_e32 v3, v2
	v_mov_b32_e32 v4, v2
	v_mov_b32_e32 v5, v2
	v_mov_b32_e32 v6, v2
	v_mov_b32_e32 v7, v2
	v_mov_b32_e32 v8, v2
	v_mov_b32_e32 v9, v2
	v_mov_b32_e32 v18, v2
	v_mov_b32_e32 v19, v2
	v_mov_b32_e32 v20, v2
	v_mov_b32_e32 v21, v2
	v_mov_b32_e32 v22, v2
	v_mov_b32_e32 v23, v2
	v_mov_b32_e32 v24, v2
	v_mov_b32_e32 v25, v2
	v_mov_b32_e32 v34, v2
	v_mov_b32_e32 v35, v2
	v_mov_b32_e32 v36, v2
	v_mov_b32_e32 v37, v2
	v_mov_b32_e32 v38, v2
	v_mov_b32_e32 v39, v2
	v_mov_b32_e32 v40, v2
	v_mov_b32_e32 v41, v2
	v_mov_b32_e32 v50, v2
	v_mov_b32_e32 v51, v2
	v_mov_b32_e32 v52, v2
	v_mov_b32_e32 v53, v2
	v_mov_b32_e32 v54, v2
	v_mov_b32_e32 v55, v2
	v_mov_b32_e32 v56, v2
	v_mov_b32_e32 v57, v2
	v_mov_b32_e32 v10, v2
	v_mov_b32_e32 v11, v2
	v_mov_b32_e32 v12, v2
	v_mov_b32_e32 v13, v2
	v_mov_b32_e32 v14, v2
	v_mov_b32_e32 v15, v2
	v_mov_b32_e32 v16, v2
	v_mov_b32_e32 v17, v2
	v_mov_b32_e32 v26, v2
	v_mov_b32_e32 v27, v2
	v_mov_b32_e32 v28, v2
	v_mov_b32_e32 v29, v2
	v_mov_b32_e32 v30, v2
	v_mov_b32_e32 v31, v2
	v_mov_b32_e32 v32, v2
	v_mov_b32_e32 v33, v2
	v_mov_b32_e32 v42, v2
	v_mov_b32_e32 v43, v2
	v_mov_b32_e32 v44, v2
	v_mov_b32_e32 v45, v2
	v_mov_b32_e32 v46, v2
	v_mov_b32_e32 v47, v2
	v_mov_b32_e32 v48, v2
	v_mov_b32_e32 v49, v2
	v_mov_b32_e32 v58, v2
	v_mov_b32_e32 v59, v2
	v_mov_b32_e32 v60, v2
	v_mov_b32_e32 v61, v2
	v_mov_b32_e32 v62, v2
	v_mov_b32_e32 v63, v2
	v_mov_b32_e32 v64, v2
	v_mov_b32_e32 v65, v2
	v_mov_b32_e32 v66, v2
	v_mov_b32_e32 v67, v2
	v_mov_b32_e32 v68, v2
	v_mov_b32_e32 v69, v2
	v_mov_b32_e32 v70, v2
	v_mov_b32_e32 v71, v2
	v_mov_b32_e32 v72, v2
	v_mov_b32_e32 v73, v2
	v_mov_b32_e32 v82, v2
	v_mov_b32_e32 v83, v2
	v_mov_b32_e32 v84, v2
	v_mov_b32_e32 v85, v2
	v_mov_b32_e32 v86, v2
	v_mov_b32_e32 v87, v2
	v_mov_b32_e32 v88, v2
	v_mov_b32_e32 v89, v2
	v_mov_b32_e32 v98, v2
	v_mov_b32_e32 v99, v2
	v_mov_b32_e32 v100, v2
	v_mov_b32_e32 v101, v2
	v_mov_b32_e32 v102, v2
	v_mov_b32_e32 v103, v2
	v_mov_b32_e32 v104, v2
	v_mov_b32_e32 v105, v2
	v_mov_b32_e32 v114, v2
	v_mov_b32_e32 v115, v2
	v_mov_b32_e32 v116, v2
	v_mov_b32_e32 v117, v2
	v_mov_b32_e32 v118, v2
	v_mov_b32_e32 v119, v2
	v_mov_b32_e32 v120, v2
	v_mov_b32_e32 v121, v2
	v_mov_b32_e32 v74, v2
	v_mov_b32_e32 v75, v2
	v_mov_b32_e32 v76, v2
	v_mov_b32_e32 v77, v2
	v_mov_b32_e32 v78, v2
	v_mov_b32_e32 v79, v2
	v_mov_b32_e32 v80, v2
	v_mov_b32_e32 v81, v2
	v_mov_b32_e32 v90, v2
	v_mov_b32_e32 v91, v2
	v_mov_b32_e32 v92, v2
	v_mov_b32_e32 v93, v2
	v_mov_b32_e32 v94, v2
	v_mov_b32_e32 v95, v2
	v_mov_b32_e32 v96, v2
	v_mov_b32_e32 v97, v2
	v_mov_b32_e32 v106, v2
	v_mov_b32_e32 v107, v2
	v_mov_b32_e32 v108, v2
	v_mov_b32_e32 v109, v2
	v_mov_b32_e32 v110, v2
	v_mov_b32_e32 v111, v2
	v_mov_b32_e32 v112, v2
	v_mov_b32_e32 v113, v2
	v_mov_b32_e32 v126, v2
	v_mov_b32_e32 v127, v2
	v_mov_b32_e32 v128, v2
	v_mov_b32_e32 v129, v2
	v_mov_b32_e32 v122, v2
	v_mov_b32_e32 v123, v2
	v_mov_b32_e32 v124, v2
	v_mov_b32_e32 v125, v2
	v_readlane_b32 s98, v235, 13
	v_readlane_b32 s99, v235, 14
	s_and_b32 s100, s54, 63
	s_and_b32 s101, s28, 3
	s_lshl_b32 s100, s100, 20
	s_lshl_b32 s101, s101, 10
	s_add_u32 s100, s100, s101
	s_add_u32 s98, s98, s100
	s_addc_u32 s99, s99, 0
	v_lshrrev_b32_e32 v240, 6, v190
	v_and_b32_e32 v241, 63, v190
	v_lshl_or_b32 v240, v240, 7, v241
	v_lshrrev_b32_e32 v241, 3, v240
	v_and_b32_e32 v240, 7, v240
	v_lshlrev_b32_e32 v241, 12, v241
	v_lshl_or_b32 v240, v240, 7, v241
	v_mov_b32_e32 v241, 0
	v_lshl_add_u64 v[238:239], s[98:99], 0, v[240:241]
	v_add_u32_e32 v240, 0x8000, v240
	v_lshl_add_u64 v[242:243], s[98:99], 0, v[240:241]
	s_mov_b32 s98, 0
.LBB0_230:
	s_add_i32 s74, s58, 2
	s_add_u32 s75, s56, 0x80
	s_addc_u32 s59, s57, 0
	s_add_i32 s78, 0, 0x10000
	s_cmp_eq_u32 s66, s58
	s_cselect_b32 s59, s29, s59
	s_cselect_b32 s58, s50, s75
	s_cselect_b32 s81, s45, s55
	s_cselect_b32 s80, s44, s51
	s_cmp_eq_u32 s74, s66
	s_cselect_b32 s98, 1, 0
	s_add_i32 s75, 0, 0x14000
	v_add_u32_e32 v156, s78, v146
	v_add_u32_e32 v172, s75, v146
	ds_read_b128 v[140:143], v156
	ds_read_b128 v[148:151], v156 offset:1024
	ds_read_b128 v[152:155], v156 offset:2048
	ds_read_b128 v[156:159], v156 offset:3072
	ds_read_b128 v[160:163], v172
	ds_read_b128 v[164:167], v172 offset:1024
	ds_read_b128 v[168:171], v172 offset:2048
	ds_read_b128 v[172:175], v172 offset:3072
	v_lshl_add_u64 v[188:189], s[56:57], 0, v[134:135]
	s_mov_b32 m0, s64
	ds_read_b128 v[176:179], v147
	ds_read_b128 v[180:183], v147 offset:1024
	ds_read_b128 v[184:187], v147 offset:2048
	ds_read_b128 v[200:203], v147 offset:3072
	ds_read_b128 v[204:207], v147 offset:4096
	ds_read_b128 v[208:211], v147 offset:5120
	ds_read_b128 v[212:215], v147 offset:6144
	ds_read_b128 v[216:219], v147 offset:7168
	global_load_lds_dwordx4 v[188:189], off
	v_lshl_add_u64 v[188:189], s[56:57], 0, v[132:133]
	s_mov_b32 m0, s65
	s_nop 0
	global_load_lds_dwordx4 v[188:189], off
	v_lshl_add_u64 v[188:189], s[56:57], 0, v[136:137]
	s_add_i32 m0, s27, 0xc000
	s_nop 0
	global_load_lds_dwordx4 v[188:189], off
	v_lshl_add_u64 v[188:189], s[56:57], 0, v[138:139]
	s_add_i32 m0, s27, 0xe000
	s_nop 0
	global_load_lds_dwordx4 v[188:189], off
	s_waitcnt vmcnt(8)
	s_waitcnt lgkmcnt(0)
	s_barrier
	s_setprio 1
	s_waitcnt lgkmcnt(0)
	v_mfma_f32_16x16x32_bf16 v[122:125], v[140:143], v[176:179], v[122:125]
	v_mfma_f32_16x16x32_bf16 v[126:129], v[152:155], v[176:179], v[126:129]
	v_mfma_f32_16x16x32_bf16 v[110:113], v[140:143], v[184:187], v[110:113]
	v_mfma_f32_16x16x32_bf16 v[106:109], v[152:155], v[184:187], v[106:109]
	v_mfma_f32_16x16x32_bf16 v[94:97], v[140:143], v[204:207], v[94:97]
	v_mfma_f32_16x16x32_bf16 v[90:93], v[152:155], v[204:207], v[90:93]
	v_mfma_f32_16x16x32_bf16 v[78:81], v[140:143], v[212:215], v[78:81]
	v_mfma_f32_16x16x32_bf16 v[74:77], v[152:155], v[212:215], v[74:77]
	v_mfma_f32_16x16x32_bf16 v[122:125], v[148:151], v[180:183], v[122:125]
	v_mfma_f32_16x16x32_bf16 v[126:129], v[156:159], v[180:183], v[126:129]
	v_mfma_f32_16x16x32_bf16 v[110:113], v[148:151], v[200:203], v[110:113]
	v_mfma_f32_16x16x32_bf16 v[106:109], v[156:159], v[200:203], v[106:109]
	v_mfma_f32_16x16x32_bf16 v[94:97], v[148:151], v[208:211], v[94:97]
	v_mfma_f32_16x16x32_bf16 v[90:93], v[156:159], v[208:211], v[90:93]
	v_mfma_f32_16x16x32_bf16 v[78:81], v[148:151], v[216:219], v[78:81]
	v_mfma_f32_16x16x32_bf16 v[74:77], v[156:159], v[216:219], v[74:77]
	s_setprio 0
	s_setprio 1
	v_mfma_f32_16x16x32_bf16 v[118:121], v[160:163], v[176:179], v[118:121]
	v_mfma_f32_16x16x32_bf16 v[114:117], v[168:171], v[176:179], v[114:117]
	v_mfma_f32_16x16x32_bf16 v[102:105], v[160:163], v[184:187], v[102:105]
	v_mfma_f32_16x16x32_bf16 v[98:101], v[168:171], v[184:187], v[98:101]
	v_mfma_f32_16x16x32_bf16 v[86:89], v[160:163], v[204:207], v[86:89]
	v_mfma_f32_16x16x32_bf16 v[82:85], v[168:171], v[204:207], v[82:85]
	v_mfma_f32_16x16x32_bf16 v[70:73], v[160:163], v[212:215], v[70:73]
	v_mfma_f32_16x16x32_bf16 v[66:69], v[168:171], v[212:215], v[66:69]
	v_mfma_f32_16x16x32_bf16 v[118:121], v[164:167], v[180:183], v[118:121]
	v_mfma_f32_16x16x32_bf16 v[114:117], v[172:175], v[180:183], v[114:117]
	v_mfma_f32_16x16x32_bf16 v[102:105], v[164:167], v[200:203], v[102:105]
	v_mfma_f32_16x16x32_bf16 v[98:101], v[172:175], v[200:203], v[98:101]
	v_mfma_f32_16x16x32_bf16 v[86:89], v[164:167], v[208:211], v[86:89]
	v_mfma_f32_16x16x32_bf16 v[82:85], v[172:175], v[208:211], v[82:85]
	v_mfma_f32_16x16x32_bf16 v[70:73], v[164:167], v[216:219], v[70:73]
	v_mfma_f32_16x16x32_bf16 v[66:69], v[172:175], v[216:219], v[66:69]
	s_setprio 0
	s_barrier
	s_add_i32 s78, s78, s5
	v_lshl_add_u64 v[188:189], s[80:81], 0, v[0:1]
	s_mov_b32 m0, s78
	ds_read_b128 v[176:179], v147 offset:16384
	ds_read_b128 v[180:183], v147 offset:17408
	ds_read_b128 v[184:187], v147 offset:18432
	ds_read_b128 v[200:203], v147 offset:19456
	ds_read_b128 v[204:207], v147 offset:20480
	ds_read_b128 v[208:211], v147 offset:21504
	ds_read_b128 v[212:215], v147 offset:22528
	ds_read_b128 v[216:219], v147 offset:23552
	global_load_lds_dwordx4 v[188:189], off
	s_add_i32 m0, s78, 0x2000
	v_lshl_add_u64 v[220:221], s[80:81], 0, v[130:131]
	s_add_u32 s80, s80, s6
	s_addc_u32 s81, s81, s7
	s_add_i32 s75, s75, s5
	global_load_lds_dwordx4 v[220:221], off
	v_lshl_add_u64 v[222:223], s[80:81], 0, v[0:1]
	s_mov_b32 m0, s75
	v_lshl_add_u64 v[224:225], s[80:81], 0, v[130:131]
	global_load_lds_dwordx4 v[222:223], off
	s_add_i32 m0, s75, 0x2000
	v_lshl_add_u64 v[226:227], s[58:59], 0, v[134:135]
	global_load_lds_dwordx4 v[224:225], off
	v_lshl_add_u64 v[228:229], s[58:59], 0, v[132:133]
	s_waitcnt vmcnt(6)
	s_waitcnt lgkmcnt(0)
	s_barrier
	s_setprio 1
	s_waitcnt lgkmcnt(0)
	v_mfma_f32_16x16x32_bf16 v[62:65], v[140:143], v[176:179], v[62:65]
	v_mfma_f32_16x16x32_bf16 v[58:61], v[152:155], v[176:179], v[58:61]
	v_mfma_f32_16x16x32_bf16 v[46:49], v[140:143], v[184:187], v[46:49]
	v_mfma_f32_16x16x32_bf16 v[42:45], v[152:155], v[184:187], v[42:45]
	v_mfma_f32_16x16x32_bf16 v[30:33], v[140:143], v[204:207], v[30:33]
	v_mfma_f32_16x16x32_bf16 v[26:29], v[152:155], v[204:207], v[26:29]
	v_mfma_f32_16x16x32_bf16 v[14:17], v[140:143], v[212:215], v[14:17]
	v_mfma_f32_16x16x32_bf16 v[10:13], v[152:155], v[212:215], v[10:13]
	v_mfma_f32_16x16x32_bf16 v[62:65], v[148:151], v[180:183], v[62:65]
	v_mfma_f32_16x16x32_bf16 v[58:61], v[156:159], v[180:183], v[58:61]
	v_mfma_f32_16x16x32_bf16 v[46:49], v[148:151], v[200:203], v[46:49]
	v_mfma_f32_16x16x32_bf16 v[42:45], v[156:159], v[200:203], v[42:45]
	v_mfma_f32_16x16x32_bf16 v[30:33], v[148:151], v[208:211], v[30:33]
	v_mfma_f32_16x16x32_bf16 v[26:29], v[156:159], v[208:211], v[26:29]
	v_mfma_f32_16x16x32_bf16 v[14:17], v[148:151], v[216:219], v[14:17]
	v_mfma_f32_16x16x32_bf16 v[10:13], v[156:159], v[216:219], v[10:13]
	s_setprio 0
	s_setprio 1
	v_mfma_f32_16x16x32_bf16 v[54:57], v[160:163], v[176:179], v[54:57]
	v_mfma_f32_16x16x32_bf16 v[50:53], v[168:171], v[176:179], v[50:53]
	v_mfma_f32_16x16x32_bf16 v[38:41], v[160:163], v[184:187], v[38:41]
	v_mfma_f32_16x16x32_bf16 v[34:37], v[168:171], v[184:187], v[34:37]
	v_mfma_f32_16x16x32_bf16 v[22:25], v[160:163], v[204:207], v[22:25]
	v_mfma_f32_16x16x32_bf16 v[18:21], v[168:171], v[204:207], v[18:21]
	v_mfma_f32_16x16x32_bf16 v[6:9], v[160:163], v[212:215], v[6:9]
	v_mfma_f32_16x16x32_bf16 v[2:5], v[168:171], v[212:215], v[2:5]
	v_mfma_f32_16x16x32_bf16 v[54:57], v[164:167], v[180:183], v[54:57]
	v_mfma_f32_16x16x32_bf16 v[50:53], v[172:175], v[180:183], v[50:53]
	v_mfma_f32_16x16x32_bf16 v[38:41], v[164:167], v[200:203], v[38:41]
	v_mfma_f32_16x16x32_bf16 v[34:37], v[172:175], v[200:203], v[34:37]
	v_mfma_f32_16x16x32_bf16 v[22:25], v[164:167], v[208:211], v[22:25]
	v_mfma_f32_16x16x32_bf16 v[18:21], v[172:175], v[208:211], v[18:21]
	v_mfma_f32_16x16x32_bf16 v[6:9], v[164:167], v[216:219], v[6:9]
	v_mfma_f32_16x16x32_bf16 v[2:5], v[172:175], v[216:219], v[2:5]
	s_setprio 0
	s_barrier
	s_add_i32 s75, 0, 0x18000
	s_add_i32 s78, 0, 0x1c000
	v_add_u32_e32 v156, s75, v146
	v_add_u32_e32 v172, s78, v146
	ds_read_b128 v[140:143], v156
	ds_read_b128 v[148:151], v156 offset:1024
	ds_read_b128 v[152:155], v156 offset:2048
	ds_read_b128 v[156:159], v156 offset:3072
	ds_read_b128 v[160:163], v172
	ds_read_b128 v[164:167], v172 offset:1024
	ds_read_b128 v[168:171], v172 offset:2048
	ds_read_b128 v[172:175], v172 offset:3072
	s_add_u32 s58, s58, s2
	s_addc_u32 s59, s59, s3
	s_mov_b32 m0, s27
	v_lshl_add_u64 v[230:231], s[58:59], 0, v[134:135]
	ds_read_b128 v[176:179], v147 offset:32768
	ds_read_b128 v[180:183], v147 offset:33792
	ds_read_b128 v[184:187], v147 offset:34816
	ds_read_b128 v[200:203], v147 offset:35840
	ds_read_b128 v[204:207], v147 offset:36864
	ds_read_b128 v[208:211], v147 offset:37888
	ds_read_b128 v[212:215], v147 offset:38912
	ds_read_b128 v[216:219], v147 offset:39936
	global_load_lds_dwordx4 v[226:227], off
	s_mov_b32 m0, s30
	s_nop 0
	global_load_lds_dwordx4 v[228:229], off
	s_mov_b32 m0, s31
	s_nop 0
	global_load_lds_dwordx4 v[230:231], off
	v_lshl_add_u64 v[230:231], s[58:59], 0, v[132:133]
	s_mov_b32 m0, s53
	s_nop 0
	global_load_lds_dwordx4 v[230:231], off
	s_waitcnt vmcnt(8)
	s_waitcnt lgkmcnt(0)
	s_barrier
	s_setprio 1
	s_waitcnt lgkmcnt(0)
	v_mfma_f32_16x16x32_bf16 v[122:125], v[140:143], v[176:179], v[122:125]
	v_mfma_f32_16x16x32_bf16 v[126:129], v[152:155], v[176:179], v[126:129]
	v_mfma_f32_16x16x32_bf16 v[110:113], v[140:143], v[184:187], v[110:113]
	v_mfma_f32_16x16x32_bf16 v[106:109], v[152:155], v[184:187], v[106:109]
	v_mfma_f32_16x16x32_bf16 v[94:97], v[140:143], v[204:207], v[94:97]
	v_mfma_f32_16x16x32_bf16 v[90:93], v[152:155], v[204:207], v[90:93]
	v_mfma_f32_16x16x32_bf16 v[78:81], v[140:143], v[212:215], v[78:81]
	v_mfma_f32_16x16x32_bf16 v[74:77], v[152:155], v[212:215], v[74:77]
	v_mfma_f32_16x16x32_bf16 v[122:125], v[148:151], v[180:183], v[122:125]
	v_mfma_f32_16x16x32_bf16 v[126:129], v[156:159], v[180:183], v[126:129]
	v_mfma_f32_16x16x32_bf16 v[110:113], v[148:151], v[200:203], v[110:113]
	v_mfma_f32_16x16x32_bf16 v[106:109], v[156:159], v[200:203], v[106:109]
	v_mfma_f32_16x16x32_bf16 v[94:97], v[148:151], v[208:211], v[94:97]
	v_mfma_f32_16x16x32_bf16 v[90:93], v[156:159], v[208:211], v[90:93]
	v_mfma_f32_16x16x32_bf16 v[78:81], v[148:151], v[216:219], v[78:81]
	v_mfma_f32_16x16x32_bf16 v[74:77], v[156:159], v[216:219], v[74:77]
	s_setprio 0
	s_setprio 1
	v_mfma_f32_16x16x32_bf16 v[118:121], v[160:163], v[176:179], v[118:121]
	v_mfma_f32_16x16x32_bf16 v[114:117], v[168:171], v[176:179], v[114:117]
	v_mfma_f32_16x16x32_bf16 v[102:105], v[160:163], v[184:187], v[102:105]
	v_mfma_f32_16x16x32_bf16 v[98:101], v[168:171], v[184:187], v[98:101]
	v_mfma_f32_16x16x32_bf16 v[86:89], v[160:163], v[204:207], v[86:89]
	v_mfma_f32_16x16x32_bf16 v[82:85], v[168:171], v[204:207], v[82:85]
	v_mfma_f32_16x16x32_bf16 v[70:73], v[160:163], v[212:215], v[70:73]
	v_mfma_f32_16x16x32_bf16 v[66:69], v[168:171], v[212:215], v[66:69]
	v_mfma_f32_16x16x32_bf16 v[118:121], v[164:167], v[180:183], v[118:121]
	v_mfma_f32_16x16x32_bf16 v[114:117], v[172:175], v[180:183], v[114:117]
	v_mfma_f32_16x16x32_bf16 v[102:105], v[164:167], v[200:203], v[102:105]
	v_mfma_f32_16x16x32_bf16 v[98:101], v[172:175], v[200:203], v[98:101]
	v_mfma_f32_16x16x32_bf16 v[86:89], v[164:167], v[208:211], v[86:89]
	v_mfma_f32_16x16x32_bf16 v[82:85], v[172:175], v[208:211], v[82:85]
	v_mfma_f32_16x16x32_bf16 v[70:73], v[164:167], v[216:219], v[70:73]
	v_mfma_f32_16x16x32_bf16 v[66:69], v[172:175], v[216:219], v[66:69]
	s_setprio 0
	s_barrier
	s_add_i32 s58, s75, s5
	v_lshl_add_u64 v[188:189], v[188:189], 0, s[24:25]
	s_mov_b32 m0, s58
	ds_read_b128 v[176:179], v147 offset:49152
	ds_read_b128 v[180:183], v147 offset:50176
	ds_read_b128 v[184:187], v147 offset:51200
	ds_read_b128 v[200:203], v147 offset:52224
	ds_read_b128 v[204:207], v147 offset:53248
	ds_read_b128 v[208:211], v147 offset:54272
	ds_read_b128 v[212:215], v147 offset:55296
	ds_read_b128 v[216:219], v147 offset:56320
	global_load_lds_dwordx4 v[188:189], off
	v_lshl_add_u64 v[188:189], v[220:221], 0, s[24:25]
	s_add_i32 m0, s58, 0x2000
	s_add_i32 s58, s78, s5
	global_load_lds_dwordx4 v[188:189], off
	v_lshl_add_u64 v[188:189], v[222:223], 0, s[24:25]
	s_mov_b32 m0, s58
	s_nop 0
	global_load_lds_dwordx4 v[188:189], off
	v_lshl_add_u64 v[188:189], v[224:225], 0, s[24:25]
	s_add_i32 m0, s58, 0x2000
	s_nop 0
	global_load_lds_dwordx4 v[188:189], off
	s_cmp_lg_u32 s98, 0
	s_cbranch_scc0 .Ltouch_skip_er
	global_load_dword v244, v[238:239], off
	global_load_dword v245, v[242:243], off
.Ltouch_skip_er:
	s_waitcnt vmcnt(6)
	s_waitcnt lgkmcnt(0)
	s_barrier
	s_setprio 1
	s_waitcnt lgkmcnt(0)
	v_mfma_f32_16x16x32_bf16 v[62:65], v[140:143], v[176:179], v[62:65]
	v_mfma_f32_16x16x32_bf16 v[58:61], v[152:155], v[176:179], v[58:61]
	v_mfma_f32_16x16x32_bf16 v[46:49], v[140:143], v[184:187], v[46:49]
	v_mfma_f32_16x16x32_bf16 v[42:45], v[152:155], v[184:187], v[42:45]
	v_mfma_f32_16x16x32_bf16 v[30:33], v[140:143], v[204:207], v[30:33]
	v_mfma_f32_16x16x32_bf16 v[26:29], v[152:155], v[204:207], v[26:29]
	v_mfma_f32_16x16x32_bf16 v[14:17], v[140:143], v[212:215], v[14:17]
	v_mfma_f32_16x16x32_bf16 v[10:13], v[152:155], v[212:215], v[10:13]
	v_mfma_f32_16x16x32_bf16 v[62:65], v[148:151], v[180:183], v[62:65]
	v_mfma_f32_16x16x32_bf16 v[58:61], v[156:159], v[180:183], v[58:61]
	v_mfma_f32_16x16x32_bf16 v[46:49], v[148:151], v[200:203], v[46:49]
	v_mfma_f32_16x16x32_bf16 v[42:45], v[156:159], v[200:203], v[42:45]
	v_mfma_f32_16x16x32_bf16 v[30:33], v[148:151], v[208:211], v[30:33]
	v_mfma_f32_16x16x32_bf16 v[26:29], v[156:159], v[208:211], v[26:29]
	v_mfma_f32_16x16x32_bf16 v[14:17], v[148:151], v[216:219], v[14:17]
	v_mfma_f32_16x16x32_bf16 v[10:13], v[156:159], v[216:219], v[10:13]
	s_setprio 0
	s_setprio 1
	v_mfma_f32_16x16x32_bf16 v[54:57], v[160:163], v[176:179], v[54:57]
	v_mfma_f32_16x16x32_bf16 v[50:53], v[168:171], v[176:179], v[50:53]
	v_mfma_f32_16x16x32_bf16 v[38:41], v[160:163], v[184:187], v[38:41]
	v_mfma_f32_16x16x32_bf16 v[34:37], v[168:171], v[184:187], v[34:37]
	v_mfma_f32_16x16x32_bf16 v[22:25], v[160:163], v[204:207], v[22:25]
	v_mfma_f32_16x16x32_bf16 v[18:21], v[168:171], v[204:207], v[18:21]
	v_mfma_f32_16x16x32_bf16 v[6:9], v[160:163], v[212:215], v[6:9]
	v_mfma_f32_16x16x32_bf16 v[2:5], v[168:171], v[212:215], v[2:5]
	v_mfma_f32_16x16x32_bf16 v[54:57], v[164:167], v[180:183], v[54:57]
	v_mfma_f32_16x16x32_bf16 v[50:53], v[172:175], v[180:183], v[50:53]
	v_mfma_f32_16x16x32_bf16 v[38:41], v[164:167], v[200:203], v[38:41]
	v_mfma_f32_16x16x32_bf16 v[34:37], v[172:175], v[200:203], v[34:37]
	v_mfma_f32_16x16x32_bf16 v[22:25], v[164:167], v[208:211], v[22:25]
	v_mfma_f32_16x16x32_bf16 v[18:21], v[172:175], v[208:211], v[18:21]
	v_mfma_f32_16x16x32_bf16 v[6:9], v[164:167], v[216:219], v[6:9]
	v_mfma_f32_16x16x32_bf16 v[2:5], v[172:175], v[216:219], v[2:5]
	s_setprio 0
	s_barrier
	s_add_u32 s56, s56, 0x100
	s_addc_u32 s57, s57, 0
	s_add_u32 s51, s51, 0x100
	s_addc_u32 s55, s55, 0
	s_cmp_ge_i32 s74, s61
	s_mov_b32 s58, s74
	s_cbranch_scc0 .LBB0_230
	v_readlane_b32 s74, v236, 30
	v_readlane_b32 s75, v236, 31
	s_mov_b32 s78, s76

	.amdhsa_kernel _Z10fwd_kernel4Args
		.amdhsa_group_segment_fixed_size 0
		.amdhsa_private_segment_fixed_size 0
		.amdhsa_kernarg_size 400
		.amdhsa_user_sgpr_count 2
		.amdhsa_user_sgpr_dispatch_ptr 0
		.amdhsa_user_sgpr_queue_ptr 0
		.amdhsa_user_sgpr_kernarg_segment_ptr 1
		.amdhsa_user_sgpr_dispatch_id 0
		.amdhsa_user_sgpr_kernarg_preload_length 0
		.amdhsa_user_sgpr_kernarg_preload_offset 0
		.amdhsa_user_sgpr_private_segment_size 0
		.amdhsa_uses_dynamic_stack 0
		.amdhsa_enable_private_segment 0
		.amdhsa_system_sgpr_workgroup_id_x 1
		.amdhsa_system_sgpr_workgroup_id_y 0
		.amdhsa_system_sgpr_workgroup_id_z 0
		.amdhsa_system_sgpr_workgroup_info 0
		.amdhsa_system_vgpr_workitem_id 2
		.amdhsa_next_free_vgpr 246
		.amdhsa_next_free_sgpr 102
		.amdhsa_accum_offset 248
		.amdhsa_reserve_vcc 1
		.amdhsa_float_round_mode_32 0
		.amdhsa_float_round_mode_16_64 0
		.amdhsa_float_denorm_mode_32 3
		.amdhsa_float_denorm_mode_16_64 3
		.amdhsa_dx10_clamp 1
		.amdhsa_ieee_mode 1
		.amdhsa_fp16_overflow 0
		.amdhsa_tg_split 0
		.amdhsa_exception_fp_ieee_invalid_op 0
		.amdhsa_exception_fp_denorm_src 0
		.amdhsa_exception_fp_ieee_div_zero 0
		.amdhsa_exception_fp_ieee_overflow 0
		.amdhsa_exception_fp_ieee_underflow 0
		.amdhsa_exception_fp_ieee_inexact 0
		.amdhsa_exception_int_div_zero 0
	.end_amdhsa_kernel

amdhsa.kernels:
  - .agpr_count:     0
    .args:
      - .offset:         0
        .size:           144
        .value_kind:     by_value
      - .offset:         144
        .size:           4
        .value_kind:     hidden_block_count_x
      - .offset:         148
        .size:           4
        .value_kind:     hidden_block_count_y
      - .offset:         152
        .size:           4
        .value_kind:     hidden_block_count_z
      - .offset:         156
        .size:           2
        .value_kind:     hidden_group_size_x
      - .offset:         158
        .size:           2
        .value_kind:     hidden_group_size_y
      - .offset:         160
        .size:           2
        .value_kind:     hidden_group_size_z
      - .offset:         162
        .size:           2
        .value_kind:     hidden_remainder_x
      - .offset:         164
        .size:           2
        .value_kind:     hidden_remainder_y
      - .offset:         166
        .size:           2
        .value_kind:     hidden_remainder_z
      - .offset:         184
        .size:           8
        .value_kind:     hidden_global_offset_x
      - .offset:         192
        .size:           8
        .value_kind:     hidden_global_offset_y
      - .offset:         200
        .size:           8
        .value_kind:     hidden_global_offset_z
      - .offset:         208
        .size:           2
        .value_kind:     hidden_grid_dims
      - .offset:         232
        .size:           8
        .value_kind:     hidden_multigrid_sync_arg
      - .offset:         264
        .size:           4
        .value_kind:     hidden_dynamic_lds_size
    .group_segment_fixed_size: 0
    .kernarg_segment_align: 8
    .kernarg_segment_size: 400
    .language:       OpenCL C
    .language_version:
      - 2
      - 0
    .max_flat_workgroup_size: 512
    .name:           _Z10fwd_kernel4Args
    .private_segment_fixed_size: 0
    .sgpr_count:     108
    .sgpr_spill_count: 216
    .symbol:         _Z10fwd_kernel4Args.kd
    .uniform_work_group_size: 1
    .uses_dynamic_stack: false
    .vgpr_count:     246
    .vgpr_spill_count: 0
    .wavefront_size: 64
